# all barrier poll loops (group and global seams) back off with s_sleep 10 between polls
# baseline (speedup 1.0000x reference)
; __device__ __forceinline__ unsigned xb_ld(unsigned* p)              { return __hip_atomic_load(p, __ATOMIC_RELAXED, __HIP_MEMORY_SCOPE_AGENT); }
; __device__ __forceinline__ void xcd_barrier_complete(unsigned* bar, unsigned x, unsigned& nloc, unsigned& nx) {
;     const unsigned G = gridDim.x * gridDim.y * gridDim.z;
;     unsigned sum, cnt, mine, sp = 0u;
;     for (;;) {
;         sum = 0u; cnt = 0u; mine = 0u;
; #pragma unroll
;         for (unsigned j = 0; j < 16; ++j) { const unsigned c = xb_ld(&bar[XB_XCNT(j)]); sum += c; cnt += (c > 0u) ? 1u : 0u; mine = (j == x) ? c : mine; }
;         if (sum == G) break;
;         __builtin_amdgcn_s_sleep(1);
;         if ((++sp & 255u) == 0u) { if (xb_ld(&bar[XB_TMO])) break; if (sp > XB_SPIN_CAP) { atomicAdd(&bar[XB_TMO], 1u); break; } }
;     }
.LBB0_167:
	global_load_dword v17, v18, s[6:7] sc1
	global_load_dword v2, v18, s[8:9] sc1
	global_load_dword v3, v18, s[12:13] sc1
	global_load_dword v4, v18, s[14:15] sc1
	global_load_dword v5, v18, s[16:17] sc1
	global_load_dword v6, v18, s[18:19] sc1
	global_load_dword v7, v18, s[20:21] sc1
	global_load_dword v8, v18, s[24:25] sc1
	global_load_dword v9, v18, s[26:27] sc1
	global_load_dword v10, v18, s[40:41] sc1
	global_load_dword v11, v18, s[46:47] sc1
	global_load_dword v12, v18, s[52:53] sc1
	global_load_dword v13, v18, s[54:55] sc1
	global_load_dword v14, v18, s[56:57] sc1
	global_load_dword v15, v18, s[58:59] sc1
	global_load_dword v16, v18, s[60:61] sc1
	s_mov_b64 s[62:63], -1
	s_mov_b64 s[64:65], -1
	s_waitcnt vmcnt(14)
	v_add_u32_e32 v19, v2, v17
	s_waitcnt vmcnt(13)
	v_add_u32_e32 v19, v19, v3
	s_waitcnt vmcnt(12)
	v_add_u32_e32 v19, v19, v4
	s_waitcnt vmcnt(11)
	v_add_u32_e32 v19, v19, v5
	s_waitcnt vmcnt(10)
	v_add_u32_e32 v19, v19, v6
	s_waitcnt vmcnt(9)
	v_add_u32_e32 v19, v19, v7
	s_waitcnt vmcnt(8)
	v_add_u32_e32 v19, v19, v8
	s_waitcnt vmcnt(7)
	v_add_u32_e32 v19, v19, v9
	s_waitcnt vmcnt(6)
	v_add_u32_e32 v19, v19, v10
	s_waitcnt vmcnt(5)
	v_add_u32_e32 v19, v19, v11
	s_waitcnt vmcnt(4)
	v_add_u32_e32 v19, v19, v12
	s_waitcnt vmcnt(3)
	v_add_u32_e32 v19, v19, v13
	s_waitcnt vmcnt(2)
	v_add_u32_e32 v19, v19, v14
	s_waitcnt vmcnt(1)
	v_add_u32_e32 v19, v19, v15
	s_waitcnt vmcnt(0)
	v_add_u32_e32 v19, v19, v16
	v_cmp_eq_u32_e32 vcc, s28, v19
	s_cbranch_vccnz .LBB0_166
	s_and_b32 s30, s29, 0xff
	s_cmp_eq_u32 s30, 0
	s_mov_b64 s[66:67], -1
	s_sleep 10
	s_cbranch_scc1 .LBB0_171
	s_and_b64 vcc, exec, s[66:67]
	s_cbranch_vccz .LBB0_166

; __device__ __forceinline__ unsigned xb_ld(unsigned* p)              { return __hip_atomic_load(p, __ATOMIC_RELAXED, __HIP_MEMORY_SCOPE_AGENT); }
; __device__ __forceinline__ unsigned xb_add(unsigned* p, unsigned v) { return __hip_atomic_fetch_add(p, v, __ATOMIC_RELAXED, __HIP_MEMORY_SCOPE_AGENT); }
; #define XB_SPIN(cond, bar) do { unsigned _sp = 0; while (cond) { __builtin_amdgcn_s_sleep(1); \
;     if ((++_sp & 255u) == 0u) { if (xb_ld(&(bar)[XB_TMO])) break; if (_sp > XB_SPIN_CAP) { atomicAdd(&(bar)[XB_TMO], 1u); break; } } } } while (0)
; __device__ __forceinline__ void xcd_barrier(const XcdBarrier& b) {
;     ...
;             else XB_SPIN(xb_ld(&bar[XB_TOPGEN]) == tg, bar);
;             __builtin_amdgcn_fence(__ATOMIC_ACQUIRE, "agent");
;             xb_add(&bar[XB_XGEN(b.x)], 1u);
;             asm volatile("s_waitcnt vmcnt(0)" ::: "memory");
;         } else {
;             asm volatile("buffer_inv sc1" ::: "memory");
;             XB_SPIN(xb_ld(&bar[XB_XGEN(b.x)]) == gen, bar);
.LBB0_182:
	s_and_b64 s[20:21], exec, s[20:21]
	s_or_b64 s[16:17], s[20:21], s[16:17]
	s_andn2_b64 s[18:19], s[18:19], exec
	s_and_b64 s[20:21], s[24:25], exec
	s_or_b64 s[18:19], s[18:19], s[20:21]
	s_andn2_b64 exec, exec, s[16:17]
	s_cbranch_execz .LBB0_189
.LBB0_183:
	s_and_b32 s24, s28, 0xff
	s_mov_b64 s[20:21], -1
	s_cmp_lg_u32 s24, 0
	s_mov_b64 s[26:27], -1
	s_sleep 10
	s_cbranch_scc0 .LBB0_186
	s_and_b64 vcc, exec, s[26:27]
	s_cbranch_vccz .LBB0_182
.LBB0_185:
	global_load_dword v4, v2, s[14:15] sc1
	s_add_i32 s28, s28, 1
	s_mov_b64 s[24:25], -1
	s_waitcnt vmcnt(0)
	v_cmp_ne_u32_e32 vcc, v4, v3
	s_orn2_b64 s[20:21], vcc, exec
	s_branch .LBB0_182

; __device__ __forceinline__ unsigned xb_ld(unsigned* p)              { return __hip_atomic_load(p, __ATOMIC_RELAXED, __HIP_MEMORY_SCOPE_AGENT); }
; __device__ __forceinline__ unsigned xb_add(unsigned* p, unsigned v) { return __hip_atomic_fetch_add(p, v, __ATOMIC_RELAXED, __HIP_MEMORY_SCOPE_AGENT); }
; #define XB_SPIN(cond, bar) do { unsigned _sp = 0; while (cond) { __builtin_amdgcn_s_sleep(1); \
;     if ((++_sp & 255u) == 0u) { if (xb_ld(&(bar)[XB_TMO])) break; if (_sp > XB_SPIN_CAP) { atomicAdd(&(bar)[XB_TMO], 1u); break; } } } } while (0)
; __device__ __forceinline__ void xcd_barrier(const XcdBarrier& b) {
;     ...
;             else XB_SPIN(xb_ld(&bar[XB_TOPGEN]) == tg, bar);
;             __builtin_amdgcn_fence(__ATOMIC_ACQUIRE, "agent");
;             xb_add(&bar[XB_XGEN(b.x)], 1u);
;             asm volatile("s_waitcnt vmcnt(0)" ::: "memory");
;         } else {
;             asm volatile("buffer_inv sc1" ::: "memory");
;             XB_SPIN(xb_ld(&bar[XB_XGEN(b.x)]) == gen, bar);
.LBB0_200:
	s_and_b32 s20, s28, 0xff
	s_cmp_lg_u32 s20, 0
	s_mov_b64 s[24:25], -1
	s_sleep 10
	s_cbranch_scc0 .LBB0_203
	s_mov_b64 s[26:27], -1
	s_and_b64 vcc, exec, s[24:25]
	s_cbranch_vccz .LBB0_199

; __device__ __forceinline__ unsigned xb_ld(unsigned* p)              { return __hip_atomic_load(p, __ATOMIC_RELAXED, __HIP_MEMORY_SCOPE_AGENT); }
; __device__ __forceinline__ void xcd_barrier_complete(unsigned* bar, unsigned x, unsigned& nloc, unsigned& nx) {
;     const unsigned G = gridDim.x * gridDim.y * gridDim.z;
;     unsigned sum, cnt, mine, sp = 0u;
;     for (;;) {
;         sum = 0u; cnt = 0u; mine = 0u;
; #pragma unroll
;         for (unsigned j = 0; j < 16; ++j) { const unsigned c = xb_ld(&bar[XB_XCNT(j)]); sum += c; cnt += (c > 0u) ? 1u : 0u; mine = (j == x) ? c : mine; }
;         if (sum == G) break;
;         __builtin_amdgcn_s_sleep(1);
;         if ((++sp & 255u) == 0u) { if (xb_ld(&bar[XB_TMO])) break; if (sp > XB_SPIN_CAP) { atomicAdd(&bar[XB_TMO], 1u); break; } }
;     }
.LBB0_478:
	global_load_dword v17, v18, s[6:7] sc1
	global_load_dword v2, v18, s[8:9] sc1
	global_load_dword v3, v18, s[14:15] sc1
	global_load_dword v4, v18, s[24:25] sc1
	global_load_dword v5, v18, s[26:27] sc1
	global_load_dword v6, v18, s[36:37] sc1
	global_load_dword v7, v18, s[40:41] sc1
	global_load_dword v8, v18, s[42:43] sc1
	global_load_dword v9, v18, s[44:45] sc1
	global_load_dword v10, v18, s[46:47] sc1
	global_load_dword v11, v18, s[52:53] sc1
	global_load_dword v12, v18, s[54:55] sc1
	global_load_dword v13, v18, s[56:57] sc1
	global_load_dword v14, v18, s[58:59] sc1
	global_load_dword v15, v18, s[60:61] sc1
	global_load_dword v16, v18, s[62:63] sc1
	s_mov_b64 s[64:65], -1
	s_mov_b64 s[66:67], -1
	s_waitcnt vmcnt(14)
	v_add_u32_e32 v19, v2, v17
	s_waitcnt vmcnt(13)
	v_add_u32_e32 v19, v19, v3
	s_waitcnt vmcnt(12)
	v_add_u32_e32 v19, v19, v4
	s_waitcnt vmcnt(11)
	v_add_u32_e32 v19, v19, v5
	s_waitcnt vmcnt(10)
	v_add_u32_e32 v19, v19, v6
	s_waitcnt vmcnt(9)
	v_add_u32_e32 v19, v19, v7
	s_waitcnt vmcnt(8)
	v_add_u32_e32 v19, v19, v8
	s_waitcnt vmcnt(7)
	v_add_u32_e32 v19, v19, v9
	s_waitcnt vmcnt(6)
	v_add_u32_e32 v19, v19, v10
	s_waitcnt vmcnt(5)
	v_add_u32_e32 v19, v19, v11
	s_waitcnt vmcnt(4)
	v_add_u32_e32 v19, v19, v12
	s_waitcnt vmcnt(3)
	v_add_u32_e32 v19, v19, v13
	s_waitcnt vmcnt(2)
	v_add_u32_e32 v19, v19, v14
	s_waitcnt vmcnt(1)
	v_add_u32_e32 v19, v19, v15
	s_waitcnt vmcnt(0)
	v_add_u32_e32 v19, v19, v16
	v_cmp_eq_u32_e32 vcc, s11, v19
	s_cbranch_vccnz .LBB0_477
	s_and_b32 s29, s28, 0xff
	s_cmp_eq_u32 s29, 0
	s_mov_b64 s[70:71], -1
	s_sleep 10
	s_cbranch_scc1 .LBB0_482
	s_and_b64 vcc, exec, s[70:71]
	s_cbranch_vccz .LBB0_476

; __device__ __forceinline__ unsigned xb_ld(unsigned* p)              { return __hip_atomic_load(p, __ATOMIC_RELAXED, __HIP_MEMORY_SCOPE_AGENT); }
; __device__ __forceinline__ unsigned xb_add(unsigned* p, unsigned v) { return __hip_atomic_fetch_add(p, v, __ATOMIC_RELAXED, __HIP_MEMORY_SCOPE_AGENT); }
; #define XB_SPIN(cond, bar) do { unsigned _sp = 0; while (cond) { __builtin_amdgcn_s_sleep(1); \
;     if ((++_sp & 255u) == 0u) { if (xb_ld(&(bar)[XB_TMO])) break; if (_sp > XB_SPIN_CAP) { atomicAdd(&(bar)[XB_TMO], 1u); break; } } } } while (0)
; __device__ __forceinline__ void xcd_barrier(const XcdBarrier& b) {
;     ...
;             else XB_SPIN(xb_ld(&bar[XB_TOPGEN]) == tg, bar);
;             __builtin_amdgcn_fence(__ATOMIC_ACQUIRE, "agent");
;             xb_add(&bar[XB_XGEN(b.x)], 1u);
;             asm volatile("s_waitcnt vmcnt(0)" ::: "memory");
;         } else {
;             asm volatile("buffer_inv sc1" ::: "memory");
;             XB_SPIN(xb_ld(&bar[XB_XGEN(b.x)]) == gen, bar);
.LBB0_494:
	s_and_b32 s28, s11, 0xff
	s_mov_b64 s[40:41], -1
	s_cmp_lg_u32 s28, 0
	s_mov_b64 s[44:45], -1
	s_sleep 10
	s_cbranch_scc0 .LBB0_497
	s_and_b64 vcc, exec, s[44:45]
	s_cbranch_vccz .LBB0_493

; __device__ __forceinline__ unsigned xb_ld(unsigned* p)              { return __hip_atomic_load(p, __ATOMIC_RELAXED, __HIP_MEMORY_SCOPE_AGENT); }
; __device__ __forceinline__ unsigned xb_add(unsigned* p, unsigned v) { return __hip_atomic_fetch_add(p, v, __ATOMIC_RELAXED, __HIP_MEMORY_SCOPE_AGENT); }
; #define XB_SPIN(cond, bar) do { unsigned _sp = 0; while (cond) { __builtin_amdgcn_s_sleep(1); \
;     if ((++_sp & 255u) == 0u) { if (xb_ld(&(bar)[XB_TMO])) break; if (_sp > XB_SPIN_CAP) { atomicAdd(&(bar)[XB_TMO], 1u); break; } } } } while (0)
; __device__ __forceinline__ void xcd_barrier(const XcdBarrier& b) {
;     ...
;             else XB_SPIN(xb_ld(&bar[XB_TOPGEN]) == tg, bar);
;             __builtin_amdgcn_fence(__ATOMIC_ACQUIRE, "agent");
;             xb_add(&bar[XB_XGEN(b.x)], 1u);
;             asm volatile("s_waitcnt vmcnt(0)" ::: "memory");
;         } else {
;             asm volatile("buffer_inv sc1" ::: "memory");
;             XB_SPIN(xb_ld(&bar[XB_XGEN(b.x)]) == gen, bar);
.LBB0_511:
	s_and_b32 s28, s11, 0xff
	s_cmp_lg_u32 s28, 0
	s_mov_b64 s[42:43], -1
	s_sleep 10
	s_cbranch_scc0 .LBB0_514
	s_mov_b64 s[44:45], -1
	s_and_b64 vcc, exec, s[42:43]
	s_cbranch_vccz .LBB0_510

; __device__ __forceinline__ unsigned xb_ld(unsigned* p)              { return __hip_atomic_load(p, __ATOMIC_RELAXED, __HIP_MEMORY_SCOPE_AGENT); }
; __device__ __forceinline__ void xcd_barrier_complete(unsigned* bar, unsigned x, unsigned& nloc, unsigned& nx) {
;     const unsigned G = gridDim.x * gridDim.y * gridDim.z;
;     unsigned sum, cnt, mine, sp = 0u;
;     for (;;) {
;         sum = 0u; cnt = 0u; mine = 0u;
; #pragma unroll
;         for (unsigned j = 0; j < 16; ++j) { const unsigned c = xb_ld(&bar[XB_XCNT(j)]); sum += c; cnt += (c > 0u) ? 1u : 0u; mine = (j == x) ? c : mine; }
;         if (sum == G) break;
;         __builtin_amdgcn_s_sleep(1);
;         if ((++sp & 255u) == 0u) { if (xb_ld(&bar[XB_TMO])) break; if (sp > XB_SPIN_CAP) { atomicAdd(&bar[XB_TMO], 1u); break; } }
;     }
.LBB0_683:
	global_load_dword v16, v17, s[6:7] sc1
	global_load_dword v1, v17, s[8:9] sc1
	global_load_dword v2, v17, s[16:17] sc1
	global_load_dword v3, v17, s[18:19] sc1
	global_load_dword v4, v17, s[20:21] sc1
	global_load_dword v5, v17, s[24:25] sc1
	global_load_dword v6, v17, s[26:27] sc1
	global_load_dword v7, v17, s[30:31] sc1
	global_load_dword v8, v17, s[36:37] sc1
	global_load_dword v9, v17, s[38:39] sc1
	global_load_dword v10, v17, s[40:41] sc1
	global_load_dword v11, v17, s[42:43] sc1
	global_load_dword v12, v17, s[44:45] sc1
	global_load_dword v13, v17, s[46:47] sc1
	global_load_dword v14, v17, s[48:49] sc1
	global_load_dword v15, v17, s[50:51] sc1
	s_mov_b64 s[52:53], -1
	s_mov_b64 s[54:55], -1
	s_waitcnt vmcnt(14)
	v_add_u32_e32 v18, v1, v16
	s_waitcnt vmcnt(13)
	v_add_u32_e32 v18, v18, v2
	s_waitcnt vmcnt(12)
	v_add_u32_e32 v18, v18, v3
	s_waitcnt vmcnt(11)
	v_add_u32_e32 v18, v18, v4
	s_waitcnt vmcnt(10)
	v_add_u32_e32 v18, v18, v5
	s_waitcnt vmcnt(9)
	v_add_u32_e32 v18, v18, v6
	s_waitcnt vmcnt(8)
	v_add_u32_e32 v18, v18, v7
	s_waitcnt vmcnt(7)
	v_add_u32_e32 v18, v18, v8
	s_waitcnt vmcnt(6)
	v_add_u32_e32 v18, v18, v9
	s_waitcnt vmcnt(5)
	v_add_u32_e32 v18, v18, v10
	s_waitcnt vmcnt(4)
	v_add_u32_e32 v18, v18, v11
	s_waitcnt vmcnt(3)
	v_add_u32_e32 v18, v18, v12
	s_waitcnt vmcnt(2)
	v_add_u32_e32 v18, v18, v13
	s_waitcnt vmcnt(1)
	v_add_u32_e32 v18, v18, v14
	s_waitcnt vmcnt(0)
	v_add_u32_e32 v18, v18, v15
	v_cmp_eq_u32_e32 vcc, s11, v18
	s_cbranch_vccnz .LBB0_682
	s_and_b32 s15, s14, 0xff
	s_cmp_eq_u32 s15, 0
	s_mov_b64 s[56:57], -1
	s_sleep 10
	s_cbranch_scc1 .LBB0_687
	s_and_b64 vcc, exec, s[56:57]
	s_cbranch_vccz .LBB0_682

; __device__ __forceinline__ unsigned xb_ld(unsigned* p)              { return __hip_atomic_load(p, __ATOMIC_RELAXED, __HIP_MEMORY_SCOPE_AGENT); }
; __device__ __forceinline__ unsigned xb_add(unsigned* p, unsigned v) { return __hip_atomic_fetch_add(p, v, __ATOMIC_RELAXED, __HIP_MEMORY_SCOPE_AGENT); }
; #define XB_SPIN(cond, bar) do { unsigned _sp = 0; while (cond) { __builtin_amdgcn_s_sleep(1); \
;     if ((++_sp & 255u) == 0u) { if (xb_ld(&(bar)[XB_TMO])) break; if (_sp > XB_SPIN_CAP) { atomicAdd(&(bar)[XB_TMO], 1u); break; } } } } while (0)
; __device__ __forceinline__ void xcd_barrier(const XcdBarrier& b) {
;     ...
;             else XB_SPIN(xb_ld(&bar[XB_TOPGEN]) == tg, bar);
;             __builtin_amdgcn_fence(__ATOMIC_ACQUIRE, "agent");
;             xb_add(&bar[XB_XGEN(b.x)], 1u);
;             asm volatile("s_waitcnt vmcnt(0)" ::: "memory");
;         } else {
;             asm volatile("buffer_inv sc1" ::: "memory");
;             XB_SPIN(xb_ld(&bar[XB_XGEN(b.x)]) == gen, bar);
.LBB0_699:
	s_and_b32 s14, s11, 0xff
	s_mov_b64 s[26:27], -1
	s_cmp_lg_u32 s14, 0
	s_mov_b64 s[36:37], -1
	s_sleep 10
	s_cbranch_scc0 .LBB0_702
	s_and_b64 vcc, exec, s[36:37]
	s_cbranch_vccz .LBB0_698

; __device__ __forceinline__ unsigned xb_ld(unsigned* p)              { return __hip_atomic_load(p, __ATOMIC_RELAXED, __HIP_MEMORY_SCOPE_AGENT); }
; __device__ __forceinline__ unsigned xb_add(unsigned* p, unsigned v) { return __hip_atomic_fetch_add(p, v, __ATOMIC_RELAXED, __HIP_MEMORY_SCOPE_AGENT); }
; #define XB_SPIN(cond, bar) do { unsigned _sp = 0; while (cond) { __builtin_amdgcn_s_sleep(1); \
;     if ((++_sp & 255u) == 0u) { if (xb_ld(&(bar)[XB_TMO])) break; if (_sp > XB_SPIN_CAP) { atomicAdd(&(bar)[XB_TMO], 1u); break; } } } } while (0)
; __device__ __forceinline__ void xcd_barrier(const XcdBarrier& b) {
;     ...
;             else XB_SPIN(xb_ld(&bar[XB_TOPGEN]) == tg, bar);
;             __builtin_amdgcn_fence(__ATOMIC_ACQUIRE, "agent");
;             xb_add(&bar[XB_XGEN(b.x)], 1u);
;             asm volatile("s_waitcnt vmcnt(0)" ::: "memory");
;         } else {
;             asm volatile("buffer_inv sc1" ::: "memory");
;             XB_SPIN(xb_ld(&bar[XB_XGEN(b.x)]) == gen, bar);
.LBB0_716:
	s_and_b32 s14, s11, 0xff
	s_cmp_lg_u32 s14, 0
	s_mov_b64 s[30:31], -1
	s_sleep 10
	s_cbranch_scc0 .LBB0_719
	s_mov_b64 s[36:37], -1
	s_and_b64 vcc, exec, s[30:31]
	s_cbranch_vccz .LBB0_715

; __device__ __forceinline__ unsigned xb_ld(unsigned* p)              { return __hip_atomic_load(p, __ATOMIC_RELAXED, __HIP_MEMORY_SCOPE_AGENT); }
; __device__ __forceinline__ void xcd_barrier_complete(unsigned* bar, unsigned x, unsigned& nloc, unsigned& nx) {
;     const unsigned G = gridDim.x * gridDim.y * gridDim.z;
;     unsigned sum, cnt, mine, sp = 0u;
;     for (;;) {
;         sum = 0u; cnt = 0u; mine = 0u;
; #pragma unroll
;         for (unsigned j = 0; j < 16; ++j) { const unsigned c = xb_ld(&bar[XB_XCNT(j)]); sum += c; cnt += (c > 0u) ? 1u : 0u; mine = (j == x) ? c : mine; }
;         if (sum == G) break;
;         __builtin_amdgcn_s_sleep(1);
;         if ((++sp & 255u) == 0u) { if (xb_ld(&bar[XB_TMO])) break; if (sp > XB_SPIN_CAP) { atomicAdd(&bar[XB_TMO], 1u); break; } }
;     }
.LBB0_787:
	global_load_dword v16, v17, s[8:9] sc1
	global_load_dword v1, v17, s[12:13] sc1
	global_load_dword v2, v17, s[16:17] sc1
	global_load_dword v3, v17, s[18:19] sc1
	global_load_dword v4, v17, s[20:21] sc1
	global_load_dword v5, v17, s[24:25] sc1
	global_load_dword v6, v17, s[26:27] sc1
	global_load_dword v7, v17, s[30:31] sc1
	global_load_dword v8, v17, s[36:37] sc1
	global_load_dword v9, v17, s[38:39] sc1
	global_load_dword v10, v17, s[40:41] sc1
	global_load_dword v11, v17, s[42:43] sc1
	global_load_dword v12, v17, s[44:45] sc1
	global_load_dword v13, v17, s[46:47] sc1
	global_load_dword v14, v17, s[48:49] sc1
	global_load_dword v15, v17, s[50:51] sc1
	s_mov_b64 s[52:53], -1
	s_mov_b64 s[54:55], -1
	s_waitcnt vmcnt(14)
	v_add_u32_e32 v18, v1, v16
	s_waitcnt vmcnt(13)
	v_add_u32_e32 v18, v18, v2
	s_waitcnt vmcnt(12)
	v_add_u32_e32 v18, v18, v3
	s_waitcnt vmcnt(11)
	v_add_u32_e32 v18, v18, v4
	s_waitcnt vmcnt(10)
	v_add_u32_e32 v18, v18, v5
	s_waitcnt vmcnt(9)
	v_add_u32_e32 v18, v18, v6
	s_waitcnt vmcnt(8)
	v_add_u32_e32 v18, v18, v7
	s_waitcnt vmcnt(7)
	v_add_u32_e32 v18, v18, v8
	s_waitcnt vmcnt(6)
	v_add_u32_e32 v18, v18, v9
	s_waitcnt vmcnt(5)
	v_add_u32_e32 v18, v18, v10
	s_waitcnt vmcnt(4)
	v_add_u32_e32 v18, v18, v11
	s_waitcnt vmcnt(3)
	v_add_u32_e32 v18, v18, v12
	s_waitcnt vmcnt(2)
	v_add_u32_e32 v18, v18, v13
	s_waitcnt vmcnt(1)
	v_add_u32_e32 v18, v18, v14
	s_waitcnt vmcnt(0)
	v_add_u32_e32 v18, v18, v15
	v_cmp_eq_u32_e32 vcc, s14, v18
	s_cbranch_vccnz .LBB0_786
	s_and_b32 s28, s15, 0xff
	s_cmp_eq_u32 s28, 0
	s_mov_b64 s[56:57], -1
	s_sleep 10
	s_cbranch_scc1 .LBB0_791
	s_and_b64 vcc, exec, s[56:57]
	s_cbranch_vccz .LBB0_786

; __device__ __forceinline__ unsigned xb_ld(unsigned* p)              { return __hip_atomic_load(p, __ATOMIC_RELAXED, __HIP_MEMORY_SCOPE_AGENT); }
; __device__ __forceinline__ unsigned xb_add(unsigned* p, unsigned v) { return __hip_atomic_fetch_add(p, v, __ATOMIC_RELAXED, __HIP_MEMORY_SCOPE_AGENT); }
; #define XB_SPIN(cond, bar) do { unsigned _sp = 0; while (cond) { __builtin_amdgcn_s_sleep(1); \
;     if ((++_sp & 255u) == 0u) { if (xb_ld(&(bar)[XB_TMO])) break; if (_sp > XB_SPIN_CAP) { atomicAdd(&(bar)[XB_TMO], 1u); break; } } } } while (0)
; __device__ __forceinline__ void xcd_barrier(const XcdBarrier& b) {
;     ...
;             else XB_SPIN(xb_ld(&bar[XB_TOPGEN]) == tg, bar);
;             __builtin_amdgcn_fence(__ATOMIC_ACQUIRE, "agent");
;             xb_add(&bar[XB_XGEN(b.x)], 1u);
;             asm volatile("s_waitcnt vmcnt(0)" ::: "memory");
;         } else {
;             asm volatile("buffer_inv sc1" ::: "memory");
;             XB_SPIN(xb_ld(&bar[XB_XGEN(b.x)]) == gen, bar);
.LBB0_803:
	s_and_b32 s15, s14, 0xff
	s_mov_b64 s[26:27], -1
	s_cmp_lg_u32 s15, 0
	s_mov_b64 s[36:37], -1
	s_sleep 10
	s_cbranch_scc0 .LBB0_806
	s_and_b64 vcc, exec, s[36:37]
	s_cbranch_vccz .LBB0_802

; __device__ __forceinline__ unsigned xb_ld(unsigned* p)              { return __hip_atomic_load(p, __ATOMIC_RELAXED, __HIP_MEMORY_SCOPE_AGENT); }
; __device__ __forceinline__ unsigned xb_add(unsigned* p, unsigned v) { return __hip_atomic_fetch_add(p, v, __ATOMIC_RELAXED, __HIP_MEMORY_SCOPE_AGENT); }
; #define XB_SPIN(cond, bar) do { unsigned _sp = 0; while (cond) { __builtin_amdgcn_s_sleep(1); \
;     if ((++_sp & 255u) == 0u) { if (xb_ld(&(bar)[XB_TMO])) break; if (_sp > XB_SPIN_CAP) { atomicAdd(&(bar)[XB_TMO], 1u); break; } } } } while (0)
; __device__ __forceinline__ void xcd_barrier(const XcdBarrier& b) {
;     ...
;             else XB_SPIN(xb_ld(&bar[XB_TOPGEN]) == tg, bar);
;             __builtin_amdgcn_fence(__ATOMIC_ACQUIRE, "agent");
;             xb_add(&bar[XB_XGEN(b.x)], 1u);
;             asm volatile("s_waitcnt vmcnt(0)" ::: "memory");
;         } else {
;             asm volatile("buffer_inv sc1" ::: "memory");
;             XB_SPIN(xb_ld(&bar[XB_XGEN(b.x)]) == gen, bar);
.LBB0_820:
	s_and_b32 s15, s14, 0xff
	s_cmp_lg_u32 s15, 0
	s_mov_b64 s[30:31], -1
	s_sleep 10
	s_cbranch_scc0 .LBB0_823
	s_mov_b64 s[36:37], -1
	s_and_b64 vcc, exec, s[30:31]
	s_cbranch_vccz .LBB0_819

; __device__ __forceinline__ unsigned xb_ld(unsigned* p)              { return __hip_atomic_load(p, __ATOMIC_RELAXED, __HIP_MEMORY_SCOPE_AGENT); }
; __device__ __forceinline__ void xcd_barrier_complete(unsigned* bar, unsigned x, unsigned& nloc, unsigned& nx) {
;     const unsigned G = gridDim.x * gridDim.y * gridDim.z;
;     unsigned sum, cnt, mine, sp = 0u;
;     for (;;) {
;         sum = 0u; cnt = 0u; mine = 0u;
; #pragma unroll
;         for (unsigned j = 0; j < 16; ++j) { const unsigned c = xb_ld(&bar[XB_XCNT(j)]); sum += c; cnt += (c > 0u) ? 1u : 0u; mine = (j == x) ? c : mine; }
;         if (sum == G) break;
;         __builtin_amdgcn_s_sleep(1);
;         if ((++sp & 255u) == 0u) { if (xb_ld(&bar[XB_TMO])) break; if (sp > XB_SPIN_CAP) { atomicAdd(&bar[XB_TMO], 1u); break; } }
;     }
.LBB0_918:
	global_load_dword v16, v17, s[6:7] sc1
	global_load_dword v1, v17, s[8:9] sc1
	global_load_dword v2, v17, s[14:15] sc1
	global_load_dword v3, v17, s[16:17] sc1
	global_load_dword v4, v17, s[20:21] sc1
	global_load_dword v5, v17, s[24:25] sc1
	global_load_dword v6, v17, s[26:27] sc1
	global_load_dword v7, v17, s[30:31] sc1
	global_load_dword v8, v17, s[36:37] sc1
	global_load_dword v9, v17, s[38:39] sc1
	global_load_dword v10, v17, s[40:41] sc1
	global_load_dword v11, v17, s[42:43] sc1
	global_load_dword v12, v17, s[44:45] sc1
	global_load_dword v13, v17, s[46:47] sc1
	global_load_dword v14, v17, s[48:49] sc1
	global_load_dword v15, v17, s[50:51] sc1
	s_mov_b64 s[52:53], -1
	s_mov_b64 s[54:55], -1
	s_waitcnt vmcnt(14)
	v_add_u32_e32 v18, v1, v16
	s_waitcnt vmcnt(13)
	v_add_u32_e32 v18, v18, v2
	s_waitcnt vmcnt(12)
	v_add_u32_e32 v18, v18, v3
	s_waitcnt vmcnt(11)
	v_add_u32_e32 v18, v18, v4
	s_waitcnt vmcnt(10)
	v_add_u32_e32 v18, v18, v5
	s_waitcnt vmcnt(9)
	v_add_u32_e32 v18, v18, v6
	s_waitcnt vmcnt(8)
	v_add_u32_e32 v18, v18, v7
	s_waitcnt vmcnt(7)
	v_add_u32_e32 v18, v18, v8
	s_waitcnt vmcnt(6)
	v_add_u32_e32 v18, v18, v9
	s_waitcnt vmcnt(5)
	v_add_u32_e32 v18, v18, v10
	s_waitcnt vmcnt(4)
	v_add_u32_e32 v18, v18, v11
	s_waitcnt vmcnt(3)
	v_add_u32_e32 v18, v18, v12
	s_waitcnt vmcnt(2)
	v_add_u32_e32 v18, v18, v13
	s_waitcnt vmcnt(1)
	v_add_u32_e32 v18, v18, v14
	s_waitcnt vmcnt(0)
	v_add_u32_e32 v18, v18, v15
	v_cmp_eq_u32_e32 vcc, s28, v18
	s_cbranch_vccnz .LBB0_917
	s_and_b32 s33, s29, 0xff
	s_cmp_eq_u32 s33, 0
	s_mov_b64 s[56:57], -1
	s_sleep 10
	s_cbranch_scc1 .LBB0_922
	s_and_b64 vcc, exec, s[56:57]
	s_cbranch_vccz .LBB0_917

; __device__ __forceinline__ unsigned xb_ld(unsigned* p)              { return __hip_atomic_load(p, __ATOMIC_RELAXED, __HIP_MEMORY_SCOPE_AGENT); }
; __device__ __forceinline__ unsigned xb_add(unsigned* p, unsigned v) { return __hip_atomic_fetch_add(p, v, __ATOMIC_RELAXED, __HIP_MEMORY_SCOPE_AGENT); }
; #define XB_SPIN(cond, bar) do { unsigned _sp = 0; while (cond) { __builtin_amdgcn_s_sleep(1); \
;     if ((++_sp & 255u) == 0u) { if (xb_ld(&(bar)[XB_TMO])) break; if (_sp > XB_SPIN_CAP) { atomicAdd(&(bar)[XB_TMO], 1u); break; } } } } while (0)
; __device__ __forceinline__ void xcd_barrier(const XcdBarrier& b) {
;     ...
;             else XB_SPIN(xb_ld(&bar[XB_TOPGEN]) == tg, bar);
;             __builtin_amdgcn_fence(__ATOMIC_ACQUIRE, "agent");
;             xb_add(&bar[XB_XGEN(b.x)], 1u);
;             asm volatile("s_waitcnt vmcnt(0)" ::: "memory");
;         } else {
;             asm volatile("buffer_inv sc1" ::: "memory");
;             XB_SPIN(xb_ld(&bar[XB_XGEN(b.x)]) == gen, bar);
.LBB0_934:
	s_and_b32 s29, s28, 0xff
	s_mov_b64 s[26:27], -1
	s_cmp_lg_u32 s29, 0
	s_mov_b64 s[36:37], -1
	s_sleep 10
	s_cbranch_scc0 .LBB0_937
	s_and_b64 vcc, exec, s[36:37]
	s_cbranch_vccz .LBB0_933

; __device__ __forceinline__ unsigned xb_ld(unsigned* p)              { return __hip_atomic_load(p, __ATOMIC_RELAXED, __HIP_MEMORY_SCOPE_AGENT); }
; __device__ __forceinline__ unsigned xb_add(unsigned* p, unsigned v) { return __hip_atomic_fetch_add(p, v, __ATOMIC_RELAXED, __HIP_MEMORY_SCOPE_AGENT); }
; #define XB_SPIN(cond, bar) do { unsigned _sp = 0; while (cond) { __builtin_amdgcn_s_sleep(1); \
;     if ((++_sp & 255u) == 0u) { if (xb_ld(&(bar)[XB_TMO])) break; if (_sp > XB_SPIN_CAP) { atomicAdd(&(bar)[XB_TMO], 1u); break; } } } } while (0)
; __device__ __forceinline__ void xcd_barrier(const XcdBarrier& b) {
;     ...
;             else XB_SPIN(xb_ld(&bar[XB_TOPGEN]) == tg, bar);
;             __builtin_amdgcn_fence(__ATOMIC_ACQUIRE, "agent");
;             xb_add(&bar[XB_XGEN(b.x)], 1u);
;             asm volatile("s_waitcnt vmcnt(0)" ::: "memory");
;         } else {
;             asm volatile("buffer_inv sc1" ::: "memory");
;             XB_SPIN(xb_ld(&bar[XB_XGEN(b.x)]) == gen, bar);
.LBB0_951:
	s_and_b32 s26, s28, 0xff
	s_cmp_lg_u32 s26, 0
	s_mov_b64 s[30:31], -1
	s_sleep 10
	s_cbranch_scc0 .LBB0_954
	s_mov_b64 s[36:37], -1
	s_and_b64 vcc, exec, s[30:31]
	s_cbranch_vccz .LBB0_950

; __device__ __forceinline__ unsigned xb_ld(unsigned* p)              { return __hip_atomic_load(p, __ATOMIC_RELAXED, __HIP_MEMORY_SCOPE_AGENT); }
; __device__ __forceinline__ void xcd_barrier_complete(unsigned* bar, unsigned x, unsigned& nloc, unsigned& nx) {
;     const unsigned G = gridDim.x * gridDim.y * gridDim.z;
;     unsigned sum, cnt, mine, sp = 0u;
;     for (;;) {
;         sum = 0u; cnt = 0u; mine = 0u;
; #pragma unroll
;         for (unsigned j = 0; j < 16; ++j) { const unsigned c = xb_ld(&bar[XB_XCNT(j)]); sum += c; cnt += (c > 0u) ? 1u : 0u; mine = (j == x) ? c : mine; }
;         if (sum == G) break;
;         __builtin_amdgcn_s_sleep(1);
;         if ((++sp & 255u) == 0u) { if (xb_ld(&bar[XB_TMO])) break; if (sp > XB_SPIN_CAP) { atomicAdd(&bar[XB_TMO], 1u); break; } }
;     }
.LBB0_1045:
	global_load_dword v16, v17, s[6:7] sc1
	global_load_dword v1, v17, s[8:9] sc1
	global_load_dword v2, v17, s[14:15] sc1
	global_load_dword v3, v17, s[18:19] sc1
	global_load_dword v4, v17, s[20:21] sc1
	global_load_dword v5, v17, s[24:25] sc1
	global_load_dword v6, v17, s[26:27] sc1
	global_load_dword v7, v17, s[30:31] sc1
	global_load_dword v8, v17, s[36:37] sc1
	global_load_dword v9, v17, s[38:39] sc1
	global_load_dword v10, v17, s[40:41] sc1
	global_load_dword v11, v17, s[42:43] sc1
	global_load_dword v12, v17, s[44:45] sc1
	global_load_dword v13, v17, s[46:47] sc1
	global_load_dword v14, v17, s[48:49] sc1
	global_load_dword v15, v17, s[50:51] sc1
	s_mov_b64 s[52:53], -1
	s_mov_b64 s[54:55], -1
	s_waitcnt vmcnt(14)
	v_add_u32_e32 v18, v1, v16
	s_waitcnt vmcnt(13)
	v_add_u32_e32 v18, v18, v2
	s_waitcnt vmcnt(12)
	v_add_u32_e32 v18, v18, v3
	s_waitcnt vmcnt(11)
	v_add_u32_e32 v18, v18, v4
	s_waitcnt vmcnt(10)
	v_add_u32_e32 v18, v18, v5
	s_waitcnt vmcnt(9)
	v_add_u32_e32 v18, v18, v6
	s_waitcnt vmcnt(8)
	v_add_u32_e32 v18, v18, v7
	s_waitcnt vmcnt(7)
	v_add_u32_e32 v18, v18, v8
	s_waitcnt vmcnt(6)
	v_add_u32_e32 v18, v18, v9
	s_waitcnt vmcnt(5)
	v_add_u32_e32 v18, v18, v10
	s_waitcnt vmcnt(4)
	v_add_u32_e32 v18, v18, v11
	s_waitcnt vmcnt(3)
	v_add_u32_e32 v18, v18, v12
	s_waitcnt vmcnt(2)
	v_add_u32_e32 v18, v18, v13
	s_waitcnt vmcnt(1)
	v_add_u32_e32 v18, v18, v14
	s_waitcnt vmcnt(0)
	v_add_u32_e32 v18, v18, v15
	v_cmp_eq_u32_e32 vcc, s28, v18
	s_cbranch_vccnz .LBB0_1044
	s_and_b32 s33, s29, 0xff
	s_cmp_eq_u32 s33, 0
	s_mov_b64 s[56:57], -1
	s_sleep 10
	s_cbranch_scc1 .LBB0_1049
	s_and_b64 vcc, exec, s[56:57]
	s_cbranch_vccz .LBB0_1044

; __device__ __forceinline__ unsigned xb_ld(unsigned* p)              { return __hip_atomic_load(p, __ATOMIC_RELAXED, __HIP_MEMORY_SCOPE_AGENT); }
; __device__ __forceinline__ void xcd_barrier_complete(unsigned* bar, unsigned x, unsigned& nloc, unsigned& nx) {
;     const unsigned G = gridDim.x * gridDim.y * gridDim.z;
;     unsigned sum, cnt, mine, sp = 0u;
;     for (;;) {
;         sum = 0u; cnt = 0u; mine = 0u;
; #pragma unroll
;         for (unsigned j = 0; j < 16; ++j) { const unsigned c = xb_ld(&bar[XB_XCNT(j)]); sum += c; cnt += (c > 0u) ? 1u : 0u; mine = (j == x) ? c : mine; }
;         if (sum == G) break;
;         __builtin_amdgcn_s_sleep(1);
;         if ((++sp & 255u) == 0u) { if (xb_ld(&bar[XB_TMO])) break; if (sp > XB_SPIN_CAP) { atomicAdd(&bar[XB_TMO], 1u); break; } }
;     }
.LBB0_1243:
	global_load_dword v16, v17, s[4:5] sc1
	global_load_dword v1, v17, s[6:7] sc1
	global_load_dword v2, v17, s[8:9] sc1
	global_load_dword v3, v17, s[10:11] sc1
	global_load_dword v4, v17, s[12:13] sc1
	global_load_dword v5, v17, s[16:17] sc1
	global_load_dword v6, v17, s[18:19] sc1
	global_load_dword v7, v17, s[20:21] sc1
	global_load_dword v8, v17, s[24:25] sc1
	global_load_dword v9, v17, s[26:27] sc1
	global_load_dword v10, v17, s[30:31] sc1
	global_load_dword v11, v17, s[36:37] sc1
	global_load_dword v12, v17, s[38:39] sc1
	global_load_dword v13, v17, s[40:41] sc1
	global_load_dword v14, v17, s[42:43] sc1
	global_load_dword v15, v17, s[44:45] sc1
	s_mov_b64 s[46:47], -1
	s_mov_b64 s[48:49], -1
	s_waitcnt vmcnt(14)
	v_add_u32_e32 v18, v1, v16
	s_waitcnt vmcnt(13)
	v_add_u32_e32 v18, v18, v2
	s_waitcnt vmcnt(12)
	v_add_u32_e32 v18, v18, v3
	s_waitcnt vmcnt(11)
	v_add_u32_e32 v18, v18, v4
	s_waitcnt vmcnt(10)
	v_add_u32_e32 v18, v18, v5
	s_waitcnt vmcnt(9)
	v_add_u32_e32 v18, v18, v6
	s_waitcnt vmcnt(8)
	v_add_u32_e32 v18, v18, v7
	s_waitcnt vmcnt(7)
	v_add_u32_e32 v18, v18, v8
	s_waitcnt vmcnt(6)
	v_add_u32_e32 v18, v18, v9
	s_waitcnt vmcnt(5)
	v_add_u32_e32 v18, v18, v10
	s_waitcnt vmcnt(4)
	v_add_u32_e32 v18, v18, v11
	s_waitcnt vmcnt(3)
	v_add_u32_e32 v18, v18, v12
	s_waitcnt vmcnt(2)
	v_add_u32_e32 v18, v18, v13
	s_waitcnt vmcnt(1)
	v_add_u32_e32 v18, v18, v14
	s_waitcnt vmcnt(0)
	v_add_u32_e32 v18, v18, v15
	v_cmp_eq_u32_e32 vcc, s28, v18
	s_cbranch_vccnz .LBB0_1242
	s_and_b32 s33, s29, 0xff
	s_cmp_eq_u32 s33, 0
	s_mov_b64 s[50:51], -1
	s_sleep 10
	s_cbranch_scc1 .LBB0_1247
	s_and_b64 vcc, exec, s[50:51]
	s_cbranch_vccz .LBB0_1242

; __device__ __forceinline__ unsigned xb_ld(unsigned* p)              { return __hip_atomic_load(p, __ATOMIC_RELAXED, __HIP_MEMORY_SCOPE_AGENT); }
; __device__ __forceinline__ unsigned xb_add(unsigned* p, unsigned v) { return __hip_atomic_fetch_add(p, v, __ATOMIC_RELAXED, __HIP_MEMORY_SCOPE_AGENT); }
; #define XB_SPIN(cond, bar) do { unsigned _sp = 0; while (cond) { __builtin_amdgcn_s_sleep(1); \
;     if ((++_sp & 255u) == 0u) { if (xb_ld(&(bar)[XB_TMO])) break; if (_sp > XB_SPIN_CAP) { atomicAdd(&(bar)[XB_TMO], 1u); break; } } } } while (0)
; __device__ __forceinline__ void xcd_barrier(const XcdBarrier& b) {
;     ...
;             else XB_SPIN(xb_ld(&bar[XB_TOPGEN]) == tg, bar);
;             __builtin_amdgcn_fence(__ATOMIC_ACQUIRE, "agent");
;             xb_add(&bar[XB_XGEN(b.x)], 1u);
;             asm volatile("s_waitcnt vmcnt(0)" ::: "memory");
;         } else {
;             asm volatile("buffer_inv sc1" ::: "memory");
;             XB_SPIN(xb_ld(&bar[XB_XGEN(b.x)]) == gen, bar);
.LBB0_1259:
	s_and_b32 s20, s26, 0xff
	s_mov_b64 s[18:19], -1
	s_cmp_lg_u32 s20, 0
	s_mov_b64 s[24:25], -1
	s_sleep 10
	s_cbranch_scc0 .LBB0_1262
	s_and_b64 vcc, exec, s[24:25]
	s_cbranch_vccz .LBB0_1258

; __device__ __forceinline__ unsigned xb_ld(unsigned* p)              { return __hip_atomic_load(p, __ATOMIC_RELAXED, __HIP_MEMORY_SCOPE_AGENT); }
; __device__ __forceinline__ unsigned xb_add(unsigned* p, unsigned v) { return __hip_atomic_fetch_add(p, v, __ATOMIC_RELAXED, __HIP_MEMORY_SCOPE_AGENT); }
; #define XB_SPIN(cond, bar) do { unsigned _sp = 0; while (cond) { __builtin_amdgcn_s_sleep(1); \
;     if ((++_sp & 255u) == 0u) { if (xb_ld(&(bar)[XB_TMO])) break; if (_sp > XB_SPIN_CAP) { atomicAdd(&(bar)[XB_TMO], 1u); break; } } } } while (0)
; __device__ __forceinline__ void xcd_barrier(const XcdBarrier& b) {
;     ...
;             else XB_SPIN(xb_ld(&bar[XB_TOPGEN]) == tg, bar);
;             __builtin_amdgcn_fence(__ATOMIC_ACQUIRE, "agent");
;             xb_add(&bar[XB_XGEN(b.x)], 1u);
;             asm volatile("s_waitcnt vmcnt(0)" ::: "memory");
;         } else {
;             asm volatile("buffer_inv sc1" ::: "memory");
;             XB_SPIN(xb_ld(&bar[XB_XGEN(b.x)]) == gen, bar);
.LBB0_1276:
	s_and_b32 s18, s26, 0xff
	s_cmp_lg_u32 s18, 0
	s_mov_b64 s[20:21], -1
	s_sleep 10
	s_cbranch_scc0 .LBB0_1279
	s_mov_b64 s[24:25], -1
	s_and_b64 vcc, exec, s[20:21]
	s_cbranch_vccz .LBB0_1275
